# v30 plus dense layer-0 loop: hoisted V reads and first three K fragment reads issued right behind the mid-iteration barrier, ahead of the four post-barrier MFMAs (LDS op order unchanged)
# speedup vs baseline: 1.0045x; 1.0045x over previous
; #define SBAR() __builtin_amdgcn_sched_barrier(0)
; #define SLOAD(i, k0) do { st_[i].vs = *reinterpret_cast<const bf16x8*>(&Vh[(size_t)((k0) + sr) * LDK + sc]); \
;     st_[i].ks = *reinterpret_cast<const bf16x8*>(&Kh[(size_t)((k0) + sr) * LDK + sc]); \
;     if (DQ == 96) st_[i].kr = *reinterpret_cast<const bf16x8*>(&Kr[(size_t)((k0) + sr2) * 32 + sc2]); } while (0)
; #define SWRITE(b, i) do { *(bf16x8*)(V_lds + (b) * SHM_V + vst0) = st_[i].vs; *(bf16x8*)(K_lds + (b) * SHM_K + kst0) = st_[i].ks; \
;     if (DQ == 96) { if (tid < 256) *(bf16x8*)(K_lds + (b) * SHM_K + kst2) = st_[i].kr; } } while (0)
; #define SWAIT() do { if (DQ == 96) asm volatile("s_waitcnt vmcnt(3)" ::: "memory"); else asm volatile("s_waitcnt vmcnt(2)" ::: "memory"); } while (0)
; #define SLOAD(i, k0) do { st_[i].vs = *reinterpret_cast<const bf16x8*>(&Vh[(size_t)((k0) + sr) * LDK + sc]); \
;     st_[i].ks = *reinterpret_cast<const bf16x8*>(&Kh[(size_t)((k0) + sr) * LDK + sc]); \
;     if (DQ == 96) st_[i].kr = *reinterpret_cast<const bf16x8*>(&Kr[(size_t)((k0) + sr2) * 32 + sc2]); } while (0)
; #define SWRITE(b, i) do { *(bf16x8*)(V_lds + (b) * SHM_V + vst0) = st_[i].vs; *(bf16x8*)(K_lds + (b) * SHM_K + kst0) = st_[i].ks; \
;     if (DQ == 96) { if (tid < 256) *(bf16x8*)(K_lds + (b) * SHM_K + kst2) = st_[i].kr; } } while (0)
; #define SWAIT() do { if (DQ == 96) asm volatile("s_waitcnt vmcnt(3)" ::: "memory"); else asm volatile("s_waitcnt vmcnt(2)" ::: "memory"); } while (0)
; template <int DQ, bool WIN, int LDQ, int LDK> ...
;     ...
;     for (int j = 1; j + 1 < NT; j += 2) {
;         SBAR(); qkt<DQ>(pB0, pB1, K_lds + SHM_K, qr, minit, r32, hi);
;         finish(pA0, pA1); SBAR();
;         SLOAD(SO, KBASE(j + 2)); SBAR();
;         pv(vb0);
;         __syncthreads(); SWAIT(); SWRITE(0, SE);
;         lsum_upd();
;         if (WIN) win_mask(pB0, pB1, qrow - KBASE(j), hi);
;         exp16(pB0);
;         __syncthreads();
;         SBAR(); qkt<DQ>(pA0, pA1, K_lds, qr, minit, r32, hi);
;         finish(pB0, pB1); SBAR();
;         if (j + 3 < NT) SLOAD(SE, KBASE(j + 3)); SBAR();
.LBB0_493:
	s_add_i32 s21, s21, 2
	ds_read_b64_tr_b16 v[42:43], v159 offset:0
	ds_read_b64_tr_b16 v[44:45], v159 offset:0x400
	ds_read_b64_tr_b16 v[46:47], v159 offset:0x800
	ds_read_b64_tr_b16 v[48:49], v159 offset:0xc00
	ds_read_b128 v[82:85], v156 offset:25600
	ds_read_b128 v[168:171], v156 offset:25632
	ds_read_b128 v[172:175], v156 offset:30208
	ds_read_b128 v[176:179], v156 offset:30240
	v_exp_f32_e32 v81, v81
	v_exp_f32_e32 v146, v66
	s_waitcnt lgkmcnt(3)
	v_mfma_f32_32x32x16_bf16 v[98:113], v[82:85], v[126:129], v[50:65]
	v_exp_f32_e32 v180, v67
	v_exp_f32_e32 v190, v68
	v_exp_f32_e32 v191, v73
	v_exp_f32_e32 v192, v74
	v_exp_f32_e32 v193, v75
	v_exp_f32_e32 v194, v80
	s_waitcnt lgkmcnt(1)
	v_mfma_f32_32x32x16_bf16 v[82:97], v[172:175], v[126:129], v[50:65]
	v_mfma_f32_32x32x16_bf16 v[98:113], v[168:171], v[122:125], v[98:113]
	ds_read_b128 v[168:171], v156 offset:25664
	ds_read_b128 v[172:175], v156 offset:25696
	ds_read_b128 v[182:185], v156 offset:30272
	ds_read_b128 v[186:189], v156 offset:30304
	v_cvt_pk_bf16_f32 v66, v138, v139
	v_cvt_pk_bf16_f32 v67, v162, v165
	v_cvt_pk_bf16_f32 v68, v163, v166
	s_waitcnt lgkmcnt(4)
	v_mfma_f32_32x32x16_bf16 v[82:97], v[176:179], v[122:125], v[82:97]
	v_exp_f32_e32 v176, v69
	v_exp_f32_e32 v177, v70
	v_exp_f32_e32 v178, v71
	v_exp_f32_e32 v179, v72
	v_cvt_pk_bf16_f32 v69, v164, v167
	v_cvt_pk_bf16_f32 v70, v140, v144
	v_cvt_pk_bf16_f32 v71, v141, v145
	s_waitcnt lgkmcnt(3)
	v_mfma_f32_32x32x16_bf16 v[98:113], v[168:171], v[118:121], v[98:113]
	v_exp_f32_e32 v168, v76
	v_exp_f32_e32 v169, v77
	v_exp_f32_e32 v170, v78
	v_exp_f32_e32 v171, v79
	v_cvt_pk_bf16_f32 v72, v142, v160
	v_cvt_pk_bf16_f32 v73, v143, v161
	v_cvt_pk_bf16_f32 v74, v146, v180
	s_waitcnt lgkmcnt(1)
	v_mfma_f32_32x32x16_bf16 v[82:97], v[182:185], v[118:121], v[82:97]
	v_cvt_pk_bf16_f32 v75, v190, v176
	v_cvt_pk_bf16_f32 v76, v177, v178
	v_cvt_pk_bf16_f32 v77, v179, v191
	v_cvt_pk_bf16_f32 v78, v192, v193
	v_cvt_pk_bf16_f32 v79, v168, v169
	v_cvt_pk_bf16_f32 v80, v170, v171
	v_cvt_pk_bf16_f32 v81, v194, v81
	v_mfma_f32_32x32x16_bf16 v[98:113], v[172:175], v[114:117], v[98:113]
	s_waitcnt lgkmcnt(0)
	v_mfma_f32_32x32x16_bf16 v[82:97], v[186:189], v[114:117], v[82:97]
	v_add_co_u32_e32 v142, vcc, s90, v148
	s_nop 1
	v_addc_co_u32_e32 v143, vcc, -1, v149, vcc
	global_load_dwordx4 v[138:141], v[142:143], off
	s_nop 0
	global_load_dwordx4 v[142:145], v[142:143], off offset:-256
	ds_read_b64_tr_b16 v[168:169], v159 offset:0x1000
	ds_read_b64_tr_b16 v[170:171], v159 offset:0x1400
	ds_read_b64_tr_b16 v[172:173], v159 offset:0x1800
	ds_read_b64_tr_b16 v[174:175], v159 offset:0x1c00
	ds_read_b64_tr_b16 v[160:161], v159 offset:0x200
	ds_read_b64_tr_b16 v[162:163], v159 offset:0x600
	ds_read_b64_tr_b16 v[164:165], v159 offset:0xa00
	ds_read_b64_tr_b16 v[166:167], v159 offset:0xe00
	v_mfma_f32_32x32x16_bf16 v[2:17], v[66:69], v[42:45], v[2:17]
	v_mfma_f32_32x32x16_bf16 v[2:17], v[70:73], v[46:49], v[2:17]
	s_waitcnt lgkmcnt(6)
	v_mfma_f32_32x32x16_bf16 v[2:17], v[74:77], v[168:171], v[2:17]
	ds_read_b64_tr_b16 v[168:169], v159 offset:0x1200
	ds_read_b64_tr_b16 v[170:171], v159 offset:0x1600
	s_waitcnt lgkmcnt(6)
	v_mfma_f32_32x32x16_bf16 v[2:17], v[78:81], v[172:175], v[2:17]
	ds_read_b64_tr_b16 v[176:177], v159 offset:0x1a00
	ds_read_b64_tr_b16 v[178:179], v159 offset:0x1e00
	s_waitcnt lgkmcnt(0)
	v_mfma_f32_32x32x16_bf16 v[18:33], v[66:69], v[160:163], v[18:33]
	s_waitcnt vmcnt(2)
	ds_write_b128 v158, v[134:137]
	ds_write_b128 v157, v[130:133] offset:16384
	v_mfma_f32_16x16x32_bf16 v[34:37], v[66:69], v[38:41], v[34:37]
	v_exp_f32_e32 v146, v98
	v_exp_f32_e32 v180, v99
	v_exp_f32_e32 v182, v100
	v_exp_f32_e32 v183, v101
	v_exp_f32_e32 v184, v102
	v_exp_f32_e32 v185, v103
	v_exp_f32_e32 v186, v104
	v_mfma_f32_32x32x16_bf16 v[18:33], v[70:73], v[164:167], v[18:33]
	v_exp_f32_e32 v187, v105
	v_exp_f32_e32 v188, v106
	v_exp_f32_e32 v189, v107
	v_exp_f32_e32 v190, v108
	v_exp_f32_e32 v191, v109
	v_exp_f32_e32 v192, v110
	v_exp_f32_e32 v193, v111
	v_mfma_f32_16x16x32_bf16 v[34:37], v[70:73], v[38:41], v[34:37]
	v_exp_f32_e32 v194, v112
	v_exp_f32_e32 v195, v113
	s_waitcnt lgkmcnt(0)
	s_barrier
	ds_read_b64_tr_b16 v[42:43], v155 offset:0
	ds_read_b64_tr_b16 v[44:45], v155 offset:0x400
	ds_read_b64_tr_b16 v[46:47], v155 offset:0x800
	ds_read_b64_tr_b16 v[48:49], v155 offset:0xc00
	ds_read_b128 v[66:69], v156 offset:16384
	ds_read_b128 v[160:163], v156 offset:16416
	ds_read_b128 v[164:167], v156 offset:20992
	v_mfma_f32_32x32x16_bf16 v[18:33], v[74:77], v[168:171], v[18:33]
	v_mfma_f32_16x16x32_bf16 v[34:37], v[74:77], v[38:41], v[34:37]
	v_mfma_f32_32x32x16_bf16 v[18:33], v[78:81], v[176:179], v[18:33]
	v_mfma_f32_16x16x32_bf16 v[34:37], v[78:81], v[38:41], v[34:37]
	ds_read_b128 v[168:171], v156 offset:21024
	v_exp_f32_e32 v82, v82
	v_exp_f32_e32 v83, v83
	s_waitcnt lgkmcnt(3)
	v_mfma_f32_32x32x16_bf16 v[98:113], v[66:69], v[126:129], v[50:65]
	v_exp_f32_e32 v84, v84
	v_exp_f32_e32 v85, v85
	v_exp_f32_e32 v89, v89
	v_exp_f32_e32 v196, v91
	v_exp_f32_e32 v197, v96
	v_exp_f32_e32 v198, v97
	s_waitcnt lgkmcnt(1)
	v_mfma_f32_32x32x16_bf16 v[66:81], v[164:167], v[126:129], v[50:65]
	v_mfma_f32_32x32x16_bf16 v[98:113], v[160:163], v[122:125], v[98:113]
	ds_read_b128 v[160:163], v156 offset:16448
	ds_read_b128 v[164:167], v156 offset:16480
	ds_read_b128 v[172:175], v156 offset:21056
	ds_read_b128 v[176:179], v156 offset:21088
	s_waitcnt lgkmcnt(4)
	v_mfma_f32_32x32x16_bf16 v[66:81], v[168:171], v[122:125], v[66:81]
	v_exp_f32_e32 v168, v86
	v_exp_f32_e32 v169, v87
	v_exp_f32_e32 v170, v88
	v_exp_f32_e32 v171, v90
	s_waitcnt lgkmcnt(3)
	v_mfma_f32_32x32x16_bf16 v[98:113], v[160:163], v[118:121], v[98:113]
	v_exp_f32_e32 v160, v92
	v_exp_f32_e32 v161, v93
	v_exp_f32_e32 v162, v94
	v_exp_f32_e32 v163, v95
	v_cvt_pk_bf16_f32 v94, v146, v180
	v_cvt_pk_bf16_f32 v95, v182, v183
	v_cvt_pk_bf16_f32 v96, v184, v185
	s_waitcnt lgkmcnt(1)
	v_mfma_f32_32x32x16_bf16 v[66:81], v[172:175], v[118:121], v[66:81]
	v_cvt_pk_bf16_f32 v97, v186, v187
	v_cvt_pk_bf16_f32 v90, v188, v189
	v_cvt_pk_bf16_f32 v91, v190, v191
	v_cvt_pk_bf16_f32 v92, v192, v193
	v_cvt_pk_bf16_f32 v93, v194, v195
	v_cvt_pk_bf16_f32 v86, v82, v83
	v_cvt_pk_bf16_f32 v87, v84, v85
	v_mfma_f32_32x32x16_bf16 v[98:113], v[164:167], v[114:117], v[98:113]
	v_cvt_pk_bf16_f32 v88, v168, v169
	v_cvt_pk_bf16_f32 v89, v170, v89
	v_cvt_pk_bf16_f32 v82, v171, v196
	v_cvt_pk_bf16_f32 v83, v160, v161
	v_cvt_pk_bf16_f32 v84, v162, v163
	v_cvt_pk_bf16_f32 v85, v197, v198
	s_waitcnt lgkmcnt(0)
	v_mfma_f32_32x32x16_bf16 v[66:81], v[176:179], v[114:117], v[66:81]
	global_load_dwordx4 v[134:137], v[148:149], off
	global_load_dwordx4 v[130:133], v[148:149], off offset:-256
	s_branch .LBB0_492
